# NSA selected-block tile body: PV MFMAs issued in the shadow of the next key-group's exp2/cvt (same scheme as FoX)
# baseline (speedup 1.0000x reference)
; template <int MODE> ...
;     ...
;             float ps = 0.f;
; #pragma unroll
;             for (int r = 0; r < 16; ++r) { s0[r] = ex2(s0[r]); s1[r] = ex2(s1[r]); ps += s0[r] + s1[r]; }
;             l += ps;
;         } else {
; #pragma unroll
;             for (int r = 0; r < 16; ++r) { s0[r] = ex2(s0[r]) * linv; s1[r] = ex2(s1[r]) * linv; }
;             float quad[8], last[8], recv[8];
; #pragma unroll
;             for (int a = 0; a < 4; ++a) {
;                 quad[a] = (s0[4 * a] + s0[4 * a + 1]) + (s0[4 * a + 2] + s0[4 * a + 3]); last[a] = s0[4 * a + 3];
;                 quad[4 + a] = (s1[4 * a] + s1[4 * a + 1]) + (s1[4 * a + 2] + s1[4 * a + 3]); last[4 + a] = s1[4 * a + 3];
;             }
; #pragma unroll
;             for (int i = 0; i < 8; ++i) recv[i] = half_other(last[i], hl);
; #pragma unroll
;             for (int i = 0; i < 8; ++i) {
;                 const float prev = (i > 0) ? recv[i > 0 ? i - 1 : 0] : carry;
;                 float v = quad[i] + (hl ? recv[i] : prev);
;                 v += __shfl_xor(v, 1); v += __shfl_xor(v, 2);
;                 if ((n & 3) == 0) lds_st<float>(L + score_ofs + (16 * kt + 2 * i + hl) * 4, v);
;             }
;             carry = recv[7];
;         }
;         if (MODE != MODE_CMP1) {
;             bf16x8 pf[4];
; #pragma unroll
;             for (int ks = 0; ks < 4; ++ks) {
;                 const int hb = 8 * (ks & 1); u32x4 w;
;                 if (ks >> 1) { w.x = cvt_pk(s1[hb], s1[hb + 1]); w.y = cvt_pk(s1[hb + 2], s1[hb + 3]); w.z = cvt_pk(s1[hb + 4], s1[hb + 5]); w.w = cvt_pk(s1[hb + 6], s1[hb + 7]); }
;                 else { w.x = cvt_pk(s0[hb], s0[hb + 1]); w.y = cvt_pk(s0[hb + 2], s0[hb + 3]); w.z = cvt_pk(s0[hb + 4], s0[hb + 5]); w.w = cvt_pk(s0[hb + 6], s0[hb + 7]); }
;                 pf[ks] = __builtin_bit_cast(bf16x8, w);
;             }
;             const lptr vb_ = Vt + (4 * hl + q4) * VP + 32 * blk + 8 * p4;
; #pragma unroll
;             for (int c_ = 0; c_ < 2; ++c_)
; #pragma unroll
;                 for (int ks_ = 0; ks_ < 4; ++ks_) {
;                     const s16x4 lo_ = tr16(vb_ + (16 * ks_) * VP + 64 * c_), hi_ = tr16(vb_ + (16 * ks_ + 8) * VP + 64 * c_);
;                     const bf16x8 vf_ = {lo_[0], lo_[1], lo_[2], lo_[3], hi_[0], hi_[1], hi_[2], hi_[3]};
;                     o[c_] = mfma32(vf_, pf[ks_], o[c_]);
;                 }
.LBB0_317:
	s_waitcnt lgkmcnt(0)
	v_exp_f32_e32 v64, v64
	v_exp_f32_e32 v65, v65
	v_exp_f32_e32 v66, v66
	v_exp_f32_e32 v67, v67
	v_exp_f32_e32 v68, v68
	v_exp_f32_e32 v69, v69
	v_exp_f32_e32 v70, v70
	v_exp_f32_e32 v71, v71
	v_cvt_pk_bf16_f32 v10, v64, v65
	v_cvt_pk_bf16_f32 v11, v66, v67
	v_pk_add_f32 v[14:15], v[64:65], v[66:67]
	v_cvt_pk_bf16_f32 v12, v68, v69
	v_pk_add_f32 v[14:15], v[14:15], v[68:69]
	v_cvt_pk_bf16_f32 v13, v70, v71
	v_pk_add_f32 v[14:15], v[14:15], v[70:71]
	v_exp_f32_e32 v72, v72
	v_exp_f32_e32 v73, v73
	v_exp_f32_e32 v74, v74
	v_exp_f32_e32 v75, v75
	v_mfma_f32_32x32x16_bf16 v[32:47], v[196:199], v[10:13], v[32:47]
	v_exp_f32_e32 v76, v76
	v_exp_f32_e32 v77, v77
	v_exp_f32_e32 v78, v78
	v_exp_f32_e32 v79, v79
	v_mfma_f32_32x32x16_bf16 v[16:31], v[238:241], v[10:13], v[16:31]
	v_cvt_pk_bf16_f32 v64, v72, v73
	v_pk_add_f32 v[14:15], v[14:15], v[72:73]
	v_cvt_pk_bf16_f32 v65, v74, v75
	v_pk_add_f32 v[14:15], v[14:15], v[74:75]
	v_cvt_pk_bf16_f32 v66, v76, v77
	v_pk_add_f32 v[14:15], v[14:15], v[76:77]
	v_cvt_pk_bf16_f32 v67, v78, v79
	v_pk_add_f32 v[14:15], v[14:15], v[78:79]
	v_exp_f32_e32 v80, v80
	v_exp_f32_e32 v81, v81
	v_exp_f32_e32 v82, v82
	v_exp_f32_e32 v83, v83
	v_mfma_f32_32x32x16_bf16 v[32:47], v[200:203], v[64:67], v[32:47]
	v_exp_f32_e32 v84, v84
	v_exp_f32_e32 v85, v85
	v_exp_f32_e32 v86, v86
	v_exp_f32_e32 v87, v87
	v_mfma_f32_32x32x16_bf16 v[16:31], v[242:245], v[64:67], v[16:31]
	v_cvt_pk_bf16_f32 v68, v80, v81
	v_pk_add_f32 v[14:15], v[14:15], v[80:81]
	v_cvt_pk_bf16_f32 v69, v82, v83
	v_pk_add_f32 v[14:15], v[14:15], v[82:83]
	v_cvt_pk_bf16_f32 v70, v84, v85
	v_pk_add_f32 v[14:15], v[14:15], v[84:85]
	v_cvt_pk_bf16_f32 v71, v86, v87
	v_pk_add_f32 v[14:15], v[14:15], v[86:87]
	v_exp_f32_e32 v88, v88
	v_exp_f32_e32 v89, v89
	v_exp_f32_e32 v90, v90
	v_exp_f32_e32 v91, v91
	v_mfma_f32_32x32x16_bf16 v[32:47], v[204:207], v[68:71], v[32:47]
	v_exp_f32_e32 v92, v92
	v_exp_f32_e32 v93, v93
	v_exp_f32_e32 v94, v94
	v_exp_f32_e32 v95, v95
	v_mfma_f32_32x32x16_bf16 v[16:31], v[246:249], v[68:71], v[16:31]
	v_cvt_pk_bf16_f32 v72, v88, v89
	v_pk_add_f32 v[14:15], v[14:15], v[88:89]
	v_cvt_pk_bf16_f32 v73, v90, v91
	v_pk_add_f32 v[14:15], v[14:15], v[90:91]
	v_cvt_pk_bf16_f32 v74, v92, v93
	v_pk_add_f32 v[14:15], v[14:15], v[92:93]
	v_cvt_pk_bf16_f32 v75, v94, v95
	v_pk_add_f32 v[14:15], v[14:15], v[94:95]
	s_nop 0
	v_add_f32_e32 v14, v14, v15
	s_nop 0
	v_mfma_f32_32x32x16_bf16 v[32:47], v[208:211], v[72:75], v[32:47]
	v_add_f32_e32 v178, v178, v14
	v_mfma_f32_32x32x16_bf16 v[16:31], v[234:237], v[72:75], v[16:31]
